# G2 residual epilogue operands staged by full-line LDS-DMA as in G3
# speedup vs baseline: 1.0642x; 1.0028x over previous
;     __device__ __forceinline__ void operator()(const f32x4 (&acc)[2][2][4][2], const Unit& u, int wr, int wc, int fr, int fq) const {
;         const int row0 = u.pm * BM + wr * 64 + fr, col0 = u.pn * BM + wc * 32 + 4 * fq;
; #pragma unroll
;         for (int ai = 0; ai < 2; ++ai) {
;             u32x2e hw[4][2][2], pw[4][2][2]; float scv[4];
; #pragma unroll
;             for (int m = 0; m < 4; ++m) { const int row = row0 + ai * HALF + m * 16; const size_t ro = (size_t)row * 2048 + col0;
;                 scv[m] = GATE ? rss_in[row] : 0.f;
; #pragma unroll
;                 for (int bj = 0; bj < 2; ++bj)
; #pragma unroll
;                     for (int n = 0; n < 2; ++n) { const size_t p = ro + bj * HALF + n * 16; hw[m][bj][n] = *(const u32x2e*)(Hin + p); if (GATE) pw[m][bj][n] = *(const u32x2e*)(PP + p); else pw[m][bj][n] = (u32x2e){0u, 0u}; } }
.Lepi2_noalign:
	s_waitcnt vmcnt(0)
	s_barrier
	v_lshlrev_b32_e32 v130, 9, v174
	v_lshrrev_b32_e32 v131, 3, v176
	v_and_b32_e32 v132, 15, v174
	v_xor_b32_e32 v131, v131, v132
	v_lshl_add_u32 v130, v131, 4, v130
	v_bfe_u32 v131, v176, 2, 1
	v_lshl_add_u32 v130, v131, 3, v130
	v_xor_b32_e32 v131, 32, v130
	v_add_u32_e32 v132, 0x10000, v130
	v_add_u32_e32 v133, 0x10000, v131
	v_lshrrev_b32_e32 v134, 5, v216
	v_and_b32_e32 v135, 31, v216
	v_xor_b32_e32 v135, v135, v134
	v_lshlrev_b32_e32 v135, 4, v135
	v_lshl_or_b32 v134, v134, 12, v135
	v_lshrrev_b32_e32 v135, 6, v183
	s_nop 0
	v_readfirstlane_b32 s7, v135
	s_lshl_b32 s8, s4, 20
	s_lshl_b32 s9, s6, 9
	s_add_i32 s8, s8, s9
	s_lshl_b32 s9, s7, 16
	s_add_i32 s8, s8, s9
	s_lshl_b32 s7, s7, 13
	s_add_u32 s10, s46, s8
	s_addc_u32 s11, s47, 0
	s_add_i32 m0, s7, 0x0
	s_add_u32 s2, s10, 0x0
	s_addc_u32 s3, s11, 0
	v_xor_b32_e32 v135, 0x0, v134
	global_load_lds_dwordx4 v135, s[2:3]
	s_add_i32 m0, s7, 0x400
	s_add_u32 s2, s10, 0x2000
	s_addc_u32 s3, s11, 0
	v_xor_b32_e32 v135, 0x20, v134
	global_load_lds_dwordx4 v135, s[2:3]
	s_add_i32 m0, s7, 0x800
	s_add_u32 s2, s10, 0x4000
	s_addc_u32 s3, s11, 0
	v_xor_b32_e32 v135, 0x40, v134
	global_load_lds_dwordx4 v135, s[2:3]
	s_add_i32 m0, s7, 0xc00
	s_add_u32 s2, s10, 0x6000
	s_addc_u32 s3, s11, 0
	v_xor_b32_e32 v135, 0x60, v134
	global_load_lds_dwordx4 v135, s[2:3]
	s_add_i32 m0, s7, 0x1000
	s_add_u32 s2, s10, 0x8000
	s_addc_u32 s3, s11, 0
	v_xor_b32_e32 v135, 0x80, v134
	global_load_lds_dwordx4 v135, s[2:3]
	s_add_i32 m0, s7, 0x1400
	s_add_u32 s2, s10, 0xa000
	s_addc_u32 s3, s11, 0
	v_xor_b32_e32 v135, 0xa0, v134
	global_load_lds_dwordx4 v135, s[2:3]
	s_add_i32 m0, s7, 0x1800
	s_add_u32 s2, s10, 0xc000
	s_addc_u32 s3, s11, 0
	v_xor_b32_e32 v135, 0xc0, v134
	global_load_lds_dwordx4 v135, s[2:3]
	s_add_i32 m0, s7, 0x1c00
	s_add_u32 s2, s10, 0xe000
	s_addc_u32 s3, s11, 0
	v_xor_b32_e32 v135, 0xe0, v134
	global_load_lds_dwordx4 v135, s[2:3]
	s_waitcnt vmcnt(0)
	s_barrier
	v_lshl_or_b32 v136, s6, 8, v176
	v_lshl_add_u32 v170, s4, 8, v174
	v_ashrrev_i32_e32 v137, 31, v136
	v_lshlrev_b64 v[178:179], 1, v[136:137]
	v_ashrrev_i32_e32 v171, 31, v170
	v_lshl_add_u64 v[138:139], s[46:47], 0, v[178:179]
	v_lshlrev_b64 v[140:141], 12, v[170:171]
	v_lshl_add_u64 v[142:143], v[138:139], 0, v[140:141]
	ds_read_b64 v[180:181], v130 offset:0
	ds_read_b64 v[192:193], v131 offset:0
	ds_read_b64 v[194:195], v130 offset:256
	ds_read_b64 v[196:197], v131 offset:256
	v_or_b32_e32 v142, 16, v170
	v_ashrrev_i32_e32 v143, 31, v142
	v_lshlrev_b64 v[168:169], 12, v[142:143]
	v_lshl_add_u64 v[142:143], v[138:139], 0, v[168:169]
	ds_read_b64 v[172:173], v130 offset:8192
	ds_read_b64 v[166:167], v131 offset:8192
	ds_read_b64 v[164:165], v130 offset:8448
	ds_read_b64 v[162:163], v131 offset:8448
	v_or_b32_e32 v142, 32, v170
	v_ashrrev_i32_e32 v143, 31, v142
	v_lshlrev_b64 v[158:159], 12, v[142:143]
	v_lshl_add_u64 v[142:143], v[138:139], 0, v[158:159]
	ds_read_b64 v[160:161], v130 offset:16384
	ds_read_b64 v[156:157], v131 offset:16384
	ds_read_b64 v[152:153], v130 offset:16640
	ds_read_b64 v[148:149], v131 offset:16640
	v_or_b32_e32 v142, 48, v170
	v_ashrrev_i32_e32 v143, 31, v142
	v_lshlrev_b64 v[144:145], 12, v[142:143]
	v_lshl_add_u64 v[142:143], v[138:139], 0, v[144:145]
	ds_read_b64 v[154:155], v130 offset:24576
	ds_read_b64 v[150:151], v131 offset:24576
	ds_read_b64 v[146:147], v130 offset:24832
	s_nop 0
	ds_read_b64 v[142:143], v131 offset:24832
	s_waitcnt vmcnt(0) lgkmcnt(0)
	s_barrier
; __device__ __forceinline__ unsigned cvt_pk_bf16(float lo, float hi) { unsigned r; asm volatile("v_cvt_pk_bf16_f32 %0, %1, %2" : "=v"(r) : "v"(lo), "v"(hi)); return r; }
;     __device__ __forceinline__ void operator()(const f32x4 (&acc)[2][2][4][2], const Unit& u, int wr, int wc, int fr, int fq) const {
;     ...
;             for (int m = 0; m < 4; ++m) { const int row = row0 + ai * HALF + m * 16; const size_t ro = (size_t)row * 2048 + col0;
;                 float sc = 1.f; if (GATE) sc = rsqrtf(scv[m] * (1.f / 2048.f) + 1e-6f);
;                 float s = 0.f;
; #pragma unroll
;                 for (int bj = 0; bj < 2; ++bj)
; #pragma unroll
;                     for (int n = 0; n < 2; ++n) { const size_t p = ro + bj * HALF + n * 16; const u32x2e hh = hw[m][bj][n], pp = pw[m][bj][n]; const f32x4 a = acc[ai][bj][m][n];
;                         f32x4 h; h[0] = __uint_as_float(hh.x << 16); h[1] = __uint_as_float(hh.x & 0xffff0000u); h[2] = __uint_as_float(hh.y << 16); h[3] = __uint_as_float(hh.y & 0xffff0000u);
;                         if (GATE) {
;                             h[0] += __builtin_amdgcn_rcpf(1.f + __expf(-sc * a[0])) * __uint_as_float(pp.x << 16); h[1] += __builtin_amdgcn_rcpf(1.f + __expf(-sc * a[1])) * __uint_as_float(pp.x & 0xffff0000u);
;                             h[2] += __builtin_amdgcn_rcpf(1.f + __expf(-sc * a[2])) * __uint_as_float(pp.y << 16); h[3] += __builtin_amdgcn_rcpf(1.f + __expf(-sc * a[3])) * __uint_as_float(pp.y & 0xffff0000u); }
;                         else h = h + a;
;                         s += (h[0] * h[0] + h[1] * h[1]) + (h[2] * h[2] + h[3] * h[3]);
;                         u32x2e o; o.x = cvt_pk_bf16(h[0], h[1]); o.y = cvt_pk_bf16(h[2], h[3]); *(u32x2e*)(Hout + p) = o; }
;                 s += __shfl_xor(s, 16); s += __shfl_xor(s, 32);
;                 if (fq == 0) atomicAdd(rss_out + row, s); }
	s_add_i32 m0, s7, 0x0
	s_add_u32 s2, s10, 0x80000
	s_addc_u32 s3, s11, 0
	v_xor_b32_e32 v135, 0x0, v134
	global_load_lds_dwordx4 v135, s[2:3]
	s_add_i32 m0, s7, 0x400
	s_add_u32 s2, s10, 0x82000
	s_addc_u32 s3, s11, 0
	v_xor_b32_e32 v135, 0x20, v134
	global_load_lds_dwordx4 v135, s[2:3]
	s_add_i32 m0, s7, 0x800
	s_add_u32 s2, s10, 0x84000
	s_addc_u32 s3, s11, 0
	v_xor_b32_e32 v135, 0x40, v134
	global_load_lds_dwordx4 v135, s[2:3]
	s_add_i32 m0, s7, 0xc00
	s_add_u32 s2, s10, 0x86000
	s_addc_u32 s3, s11, 0
	v_xor_b32_e32 v135, 0x60, v134
	global_load_lds_dwordx4 v135, s[2:3]
	s_add_i32 m0, s7, 0x1000
	s_add_u32 s2, s10, 0x88000
	s_addc_u32 s3, s11, 0
	v_xor_b32_e32 v135, 0x80, v134
	global_load_lds_dwordx4 v135, s[2:3]
	s_add_i32 m0, s7, 0x1400
	s_add_u32 s2, s10, 0x8a000
	s_addc_u32 s3, s11, 0
	v_xor_b32_e32 v135, 0xa0, v134
	global_load_lds_dwordx4 v135, s[2:3]
	s_add_i32 m0, s7, 0x1800
	s_add_u32 s2, s10, 0x8c000
	s_addc_u32 s3, s11, 0
	v_xor_b32_e32 v135, 0xc0, v134
	global_load_lds_dwordx4 v135, s[2:3]
	s_add_i32 m0, s7, 0x1c00
	s_add_u32 s2, s10, 0x8e000
	s_addc_u32 s3, s11, 0
	v_xor_b32_e32 v135, 0xe0, v134
	global_load_lds_dwordx4 v135, s[2:3]
	s_waitcnt vmcnt(0)
	v_lshlrev_b32_e32 v198, 16, v180
	v_and_b32_e32 v199, 0xffff0000, v180
	v_lshlrev_b32_e32 v180, 16, v181
	v_and_b32_e32 v181, 0xffff0000, v181
	v_pk_add_f32 v[128:129], v[128:129], v[180:181]
	v_pk_add_f32 v[126:127], v[126:127], v[198:199]
	v_mul_f32_e32 v181, v129, v129
	v_mul_f32_e32 v180, v127, v127
	v_fmac_f32_e32 v180, v126, v126
	v_fmac_f32_e32 v181, v128, v128
	v_cvt_pk_bf16_f32 v126, v126, v127
	v_cvt_pk_bf16_f32 v127, v128, v129
	v_lshl_add_u64 v[128:129], s[48:49], 0, v[140:141]
	v_lshl_add_u64 v[128:129], v[128:129], 0, v[178:179]
	global_store_dwordx2 v[128:129], v[126:127], off
	v_lshlrev_b32_e32 v126, 16, v192
	v_and_b32_e32 v127, 0xffff0000, v192
	v_pk_add_f32 v[122:123], v[122:123], v[126:127]
	v_lshlrev_b32_e32 v178, 16, v193
	v_and_b32_e32 v179, 0xffff0000, v193
	v_mul_f32_e32 v126, v123, v123
	v_pk_add_f32 v[124:125], v[124:125], v[178:179]
	v_fmac_f32_e32 v126, v122, v122
	v_cvt_pk_bf16_f32 v122, v122, v123
	v_cvt_pk_bf16_f32 v123, v124, v125
	v_mul_f32_e32 v127, v125, v125
	global_store_dwordx2 v[128:129], v[122:123], off offset:32
	v_lshlrev_b32_e32 v122, 16, v194
	v_and_b32_e32 v123, 0xffff0000, v194
	v_fmac_f32_e32 v127, v124, v124
	v_lshlrev_b32_e32 v124, 16, v195
	v_and_b32_e32 v125, 0xffff0000, v195
	v_pk_add_f32 v[118:119], v[118:119], v[122:123]
	v_pk_add_f32 v[120:121], v[120:121], v[124:125]
	v_mul_f32_e32 v122, v119, v119
	v_fmac_f32_e32 v122, v118, v118
	v_mul_f32_e32 v123, v121, v121
	v_cvt_pk_bf16_f32 v118, v118, v119
	v_cvt_pk_bf16_f32 v119, v120, v121
	v_fmac_f32_e32 v123, v120, v120
	global_store_dwordx2 v[128:129], v[118:119], off offset:256
	v_lshlrev_b32_e32 v118, 16, v196
	v_and_b32_e32 v119, 0xffff0000, v196
	v_lshlrev_b32_e32 v120, 16, v197
	v_and_b32_e32 v121, 0xffff0000, v197
	v_pk_add_f32 v[116:117], v[116:117], v[120:121]
	v_pk_add_f32 v[118:119], v[114:115], v[118:119]
	v_mul_f32_e32 v115, v117, v117
	v_mul_f32_e32 v114, v119, v119
	v_fmac_f32_e32 v114, v118, v118
	v_fmac_f32_e32 v115, v116, v116
	v_cvt_pk_bf16_f32 v118, v118, v119
	v_cvt_pk_bf16_f32 v119, v116, v117
	v_and_b32_e32 v116, 64, v216
	v_add_f32_e32 v180, v180, v181
	v_add_f32_e32 v126, v126, v127
	v_add_f32_e32 v114, v114, v115
	v_xor_b32_e32 v115, 16, v216
	v_add_u32_e32 v117, 64, v116
	v_add_f32_e32 v126, v180, v126
	v_add_f32_e32 v122, v122, v123
	v_cmp_lt_i32_e32 vcc, v115, v117
	v_add_f32_e32 v122, v126, v122
	v_add_f32_e32 v114, v122, v114
	v_cndmask_b32_e32 v115, v216, v115, vcc
	v_lshlrev_b32_e32 v116, 2, v115
	ds_bpermute_b32 v115, v116, v114
	global_store_dwordx2 v[128:129], v[118:119], off offset:288
	s_waitcnt lgkmcnt(0)
	v_add_f32_e32 v118, v114, v115
	v_xor_b32_e32 v114, 32, v216
	v_cmp_lt_i32_e32 vcc, v114, v117
	s_nop 1
	v_cndmask_b32_e32 v114, v216, v114, vcc
	v_lshlrev_b32_e32 v117, 2, v114
	ds_bpermute_b32 v119, v117, v118
	v_lshl_add_u64 v[114:115], v[170:171], 2, s[50:51]
	s_and_saveexec_b64 s[0:1], s[42:43]
	s_cbranch_execz .LBB0_95
	s_waitcnt lgkmcnt(0)
	v_add_f32_e32 v118, v118, v119
	global_atomic_add_f32 v[114:115], v118, off

; __device__ __forceinline__ unsigned cvt_pk_bf16(float lo, float hi) { unsigned r; asm volatile("v_cvt_pk_bf16_f32 %0, %1, %2" : "=v"(r) : "v"(lo), "v"(hi)); return r; }
;     __device__ __forceinline__ void operator()(const f32x4 (&acc)[2][2][4][2], const Unit& u, int wr, int wc, int fr, int fq) const {
;     ...
;             for (int m = 0; m < 4; ++m) { const int row = row0 + ai * HALF + m * 16; const size_t ro = (size_t)row * 2048 + col0;
;                 scv[m] = GATE ? rss_in[row] : 0.f;
; #pragma unroll
;                 for (int bj = 0; bj < 2; ++bj)
; #pragma unroll
;                     for (int n = 0; n < 2; ++n) { const size_t p = ro + bj * HALF + n * 16; hw[m][bj][n] = *(const u32x2e*)(Hin + p); if (GATE) pw[m][bj][n] = *(const u32x2e*)(PP + p); else pw[m][bj][n] = (u32x2e){0u, 0u}; } }
; #pragma unroll
;             for (int m = 0; m < 4; ++m) { const int row = row0 + ai * HALF + m * 16; const size_t ro = (size_t)row * 2048 + col0;
;                 float sc = 1.f; if (GATE) sc = rsqrtf(scv[m] * (1.f / 2048.f) + 1e-6f);
;                 float s = 0.f;
; #pragma unroll
;                 for (int bj = 0; bj < 2; ++bj)
; #pragma unroll
;                     for (int n = 0; n < 2; ++n) { const size_t p = ro + bj * HALF + n * 16; const u32x2e hh = hw[m][bj][n], pp = pw[m][bj][n]; const f32x4 a = acc[ai][bj][m][n];
;                         f32x4 h; h[0] = __uint_as_float(hh.x << 16); h[1] = __uint_as_float(hh.x & 0xffff0000u); h[2] = __uint_as_float(hh.y << 16); h[3] = __uint_as_float(hh.y & 0xffff0000u);
;                         if (GATE) {
;                             h[0] += __builtin_amdgcn_rcpf(1.f + __expf(-sc * a[0])) * __uint_as_float(pp.x << 16); h[1] += __builtin_amdgcn_rcpf(1.f + __expf(-sc * a[1])) * __uint_as_float(pp.x & 0xffff0000u);
;                             h[2] += __builtin_amdgcn_rcpf(1.f + __expf(-sc * a[2])) * __uint_as_float(pp.y << 16); h[3] += __builtin_amdgcn_rcpf(1.f + __expf(-sc * a[3])) * __uint_as_float(pp.y & 0xffff0000u); }
;                         else h = h + a;
;                         s += (h[0] * h[0] + h[1] * h[1]) + (h[2] * h[2] + h[3] * h[3]);
;                         u32x2e o; o.x = cvt_pk_bf16(h[0], h[1]); o.y = cvt_pk_bf16(h[2], h[3]); *(u32x2e*)(Hout + p) = o; }
;                 s += __shfl_xor(s, 16); s += __shfl_xor(s, 32);
;                 if (fq == 0) atomicAdd(rss_out + row, s); }
.LBB0_101:
	s_or_b64 exec, exec, s[0:1]
	s_waitcnt vmcnt(16)
	s_barrier
	s_mov_b64 s[0:1], 0x80000
	v_lshl_add_u64 v[100:101], v[140:141], 0, s[0:1]
	s_waitcnt lgkmcnt(0)
	v_lshl_add_u64 v[66:67], v[138:139], 0, v[100:101]
	ds_read_b64 v[102:103], v130 offset:0
	ds_read_b64 v[104:105], v131 offset:0
	ds_read_b64 v[98:99], v130 offset:256
	ds_read_b64 v[96:97], v131 offset:256
	s_mov_b64 s[0:1], 0x90000
	v_lshl_add_u64 v[92:93], v[140:141], 0, s[0:1]
	s_mov_b64 s[0:1], 0xa0000
	v_lshl_add_u64 v[66:67], v[138:139], 0, v[92:93]
	v_lshl_add_u64 v[82:83], v[140:141], 0, s[0:1]
	s_mov_b64 s[0:1], 0xb0000
	ds_read_b64 v[94:95], v130 offset:8192
	ds_read_b64 v[90:91], v131 offset:8192
	ds_read_b64 v[88:89], v130 offset:8448
	ds_read_b64 v[86:87], v131 offset:8448
	v_lshl_add_u64 v[66:67], v[138:139], 0, v[82:83]
	v_lshl_add_u64 v[68:69], v[140:141], 0, s[0:1]
	ds_read_b64 v[84:85], v130 offset:16384
	ds_read_b64 v[80:81], v131 offset:16384
	ds_read_b64 v[78:79], v130 offset:16640
	ds_read_b64 v[74:75], v131 offset:16640
	v_lshl_add_u64 v[66:67], v[138:139], 0, v[68:69]
	ds_read_b64 v[76:77], v130 offset:24576
	ds_read_b64 v[72:73], v131 offset:24576
	ds_read_b64 v[70:71], v130 offset:24832
	s_nop 0
	ds_read_b64 v[66:67], v131 offset:24832
	s_waitcnt vmcnt(0) lgkmcnt(0)
	s_waitcnt vmcnt(15)
	v_lshlrev_b32_e32 v106, 16, v102
	v_and_b32_e32 v107, 0xffff0000, v102
	v_lshlrev_b32_e32 v102, 16, v103
	v_and_b32_e32 v103, 0xffff0000, v103
	v_pk_add_f32 v[64:65], v[64:65], v[102:103]
	v_pk_add_f32 v[62:63], v[62:63], v[106:107]
	v_mul_f32_e32 v103, v65, v65
	v_mul_f32_e32 v102, v63, v63
	v_fmac_f32_e32 v102, v62, v62
	v_fmac_f32_e32 v103, v64, v64
	v_add_f32_e32 v106, v102, v103
	v_cvt_pk_bf16_f32 v102, v62, v63
	v_cvt_pk_bf16_f32 v103, v64, v65
	s_waitcnt vmcnt(14)
	v_lshlrev_b32_e32 v64, 16, v104
	v_and_b32_e32 v65, 0xffff0000, v104
	v_lshl_add_u64 v[62:63], s[48:49], 0, v[100:101]
	v_pk_add_f32 v[58:59], v[58:59], v[64:65]
	v_lshl_add_u64 v[62:63], v[136:137], 1, v[62:63]
	v_lshlrev_b32_e32 v100, 16, v105
	v_and_b32_e32 v101, 0xffff0000, v105
	v_mul_f32_e32 v64, v59, v59
	global_store_dwordx2 v[62:63], v[102:103], off
	v_pk_add_f32 v[60:61], v[60:61], v[100:101]
	v_fmac_f32_e32 v64, v58, v58
	v_cvt_pk_bf16_f32 v58, v58, v59
	v_cvt_pk_bf16_f32 v59, v60, v61
	v_mul_f32_e32 v65, v61, v61
	global_store_dwordx2 v[62:63], v[58:59], off offset:32
	s_waitcnt vmcnt(15)
	v_lshlrev_b32_e32 v58, 16, v98
	v_and_b32_e32 v59, 0xffff0000, v98
	v_fmac_f32_e32 v65, v60, v60
	v_lshlrev_b32_e32 v60, 16, v99
	v_and_b32_e32 v61, 0xffff0000, v99
	v_pk_add_f32 v[54:55], v[54:55], v[58:59]
	v_pk_add_f32 v[56:57], v[56:57], v[60:61]
	v_mul_f32_e32 v58, v55, v55
	v_fmac_f32_e32 v58, v54, v54
	v_mul_f32_e32 v59, v57, v57
	v_cvt_pk_bf16_f32 v54, v54, v55
	v_cvt_pk_bf16_f32 v55, v56, v57
	v_fmac_f32_e32 v59, v56, v56
	global_store_dwordx2 v[62:63], v[54:55], off offset:256
	s_waitcnt vmcnt(15)
	v_lshlrev_b32_e32 v54, 16, v96
	v_and_b32_e32 v55, 0xffff0000, v96
	v_lshlrev_b32_e32 v56, 16, v97
	v_and_b32_e32 v57, 0xffff0000, v97
	v_pk_add_f32 v[52:53], v[52:53], v[56:57]
	v_pk_add_f32 v[50:51], v[50:51], v[54:55]
	v_add_f32_e32 v64, v64, v65
	v_mul_f32_e32 v54, v51, v51
	v_mul_f32_e32 v55, v53, v53
	v_add_f32_e32 v64, v106, v64
	v_add_f32_e32 v58, v58, v59
	v_fmac_f32_e32 v54, v50, v50
	v_fmac_f32_e32 v55, v52, v52
	v_add_f32_e32 v58, v64, v58
	v_add_f32_e32 v54, v54, v55
	v_add_f32_e32 v54, v58, v54
	v_cvt_pk_bf16_f32 v50, v50, v51
	v_cvt_pk_bf16_f32 v51, v52, v53
	global_store_dwordx2 v[62:63], v[50:51], off offset:288
	ds_bpermute_b32 v50, v116, v54
	s_waitcnt lgkmcnt(0)
	v_add_f32_e32 v50, v54, v50
	ds_bpermute_b32 v51, v117, v50
	s_and_saveexec_b64 s[0:1], s[42:43]
	s_cbranch_execz .LBB0_103
	s_waitcnt lgkmcnt(0)
	v_add_f32_e32 v50, v50, v51
	global_atomic_add_f32 v[114:115], v50, off offset:512
